# B3: wide row loops + decode GEMM tile loads the 128 padding rows with a single lane (a third less LDS-DMA traffic on the decode path)
# baseline (speedup 1.0000x reference)
.LBB0_242:
	s_or_b64 exec, exec, s[0:1]
	v_mov_b32_e32 v74, v133
	s_barrier
	v_readlane_b32 s53, v214, 24
	v_ashrrev_i32_e32 v12, 6, v74
	v_bfe_u32 v4, v74, 3, 3
	v_lshl_or_b32 v2, v12, 4, v4
	v_add_u32_e32 v0, s53, v2
	v_bfe_u32 v5, v74, 4, 2
	v_ashrrev_i32_e32 v1, 31, v0
	v_xor_b32_e32 v5, v5, v74
	v_lshlrev_b64 v[0:1], 11, v[0:1]
	v_lshlrev_b32_e32 v5, 4, v5
	v_lshl_add_u64 v[0:1], s[40:41], 0, v[0:1]
	v_or_b32_e32 v13, 8, v2
	v_lshl_or_b32 v4, v12, 5, v4
	v_and_b32_e32 v64, 0x70, v5
	v_add_u32_e32 v2, s53, v13
	v_ashrrev_i32_e32 v5, 31, v4
	v_readlane_b32 s0, v214, 4
	v_lshl_add_u64 v[70:71], v[0:1], 0, v[64:65]
	v_lshrrev_b32_e32 v0, 1, v13
	v_ashrrev_i32_e32 v3, 31, v2
	v_lshlrev_b64 v[6:7], 11, v[4:5]
	v_readlane_b32 s1, v214, 5
	v_xor_b32_e32 v0, v0, v74
	v_lshlrev_b64 v[2:3], 11, v[2:3]
	v_lshl_add_u64 v[6:7], s[0:1], 0, v[6:7]
	v_lshlrev_b32_e32 v0, 4, v0
	v_lshl_add_u64 v[2:3], s[40:41], 0, v[2:3]
	v_lshl_add_u64 v[66:67], v[6:7], 0, v[64:65]
	v_lshrrev_b32_e32 v4, 1, v4
	v_and_b32_e32 v64, 0x70, v0
	v_bitop3_b32 v4, v4, v74, 4 bitop3:0x36
	v_lshl_add_u64 v[72:73], v[2:3], 0, v[64:65]
	v_lshlrev_b32_e32 v3, 12, v12
	v_lshlrev_b32_e32 v4, 4, v4
	v_add_u32_e32 v127, 0, v3
	s_mov_b64 s[0:1], 0x2000000
	v_and_b32_e32 v4, 0x70, v4
	v_mov_b32_e32 v5, v65
	s_waitcnt vmcnt(0)
	v_readfirstlane_b32 s38, v127
	v_add_u32_e32 v126, 0x400, v127
	v_lshl_add_u64 v[8:9], v[66:67], 0, s[0:1]
	v_lshl_add_u64 v[68:69], v[6:7], 0, v[4:5]
	s_mov_b64 s[0:1], 0x2004000
	s_waitcnt lgkmcnt(0)
	s_barrier
	v_lshrrev_b32_e32 v182, 6, v133
	s_nop 0
	v_readfirstlane_b32 s32, v182
	s_nop 0
	s_cmp_lt_u32 s32, 4
	s_cselect_b64 vcc, -1, 1
	s_mov_b32 m0, s38
	v_readfirstlane_b32 s37, v126
	v_lshl_add_u64 v[4:5], v[68:69], 0, s[0:1]
	s_mov_b64 exec, vcc
	global_load_lds_dwordx4 v[8:9], off
	s_mov_b64 exec, -1
	s_mov_b32 m0, s37
	v_add_u32_e32 v124, 0x800, v127
	s_mov_b64 exec, vcc
	global_load_lds_dwordx4 v[4:5], off
	s_mov_b64 exec, -1
	v_lshlrev_b32_e32 v4, 11, v12
	s_mov_b64 s[0:1], 0x2008000
	v_readfirstlane_b32 s36, v124
	v_add_u32_e32 v122, 0xc00, v127
	v_add_u32_e32 v5, 0, v4
	v_lshl_add_u64 v[6:7], v[66:67], 0, s[0:1]
	s_mov_b64 s[0:1], 0x200c000
	s_mov_b32 m0, s36
	v_readfirstlane_b32 s35, v122
	v_add_u32_e32 v125, 0x8000, v5
	v_lshl_add_u64 v[10:11], v[68:69], 0, s[0:1]
	s_mov_b64 exec, vcc
	global_load_lds_dwordx4 v[6:7], off
	s_mov_b64 exec, -1
	s_mov_b32 m0, s35
	v_readfirstlane_b32 s39, v125
	v_add_u32_e32 v123, 0x8400, v5
	s_mov_b64 exec, vcc
	global_load_lds_dwordx4 v[10:11], off
	s_mov_b64 exec, -1
	s_mov_b32 m0, s39
	v_readfirstlane_b32 s40, v123
	v_add_u32_e32 v116, 0xc000, v127
	global_load_lds_dwordx4 v[70:71], off
	s_mov_b32 m0, s40
	s_mov_b64 s[0:1], 0x2000080
	v_readfirstlane_b32 s23, v116
	v_add_u32_e32 v117, 0xc400, v127
	global_load_lds_dwordx4 v[72:73], off
	v_lshl_add_u64 v[0:1], v[66:67], 0, s[0:1]
	s_mov_b32 m0, s23
	s_mov_b64 s[0:1], 0x2004080
	v_readfirstlane_b32 s24, v117
	v_add_u32_e32 v118, 0xc800, v127
	s_mov_b64 exec, vcc
	global_load_lds_dwordx4 v[0:1], off
	s_mov_b64 exec, -1
	v_lshl_add_u64 v[0:1], v[68:69], 0, s[0:1]
	s_mov_b32 m0, s24
	s_mov_b64 s[0:1], 0x2008080
	v_readfirstlane_b32 s28, v118
	v_add_u32_e32 v119, 0xcc00, v127
	s_mov_b64 exec, vcc
	global_load_lds_dwordx4 v[0:1], off
	s_mov_b64 exec, -1
	v_lshl_add_u64 v[0:1], v[66:67], 0, s[0:1]
	s_mov_b32 m0, s28
	s_mov_b64 s[0:1], 0x200c080
	v_readfirstlane_b32 s29, v119
	v_add_u32_e32 v120, s85, v4
	s_mov_b64 exec, vcc
	global_load_lds_dwordx4 v[0:1], off
	s_mov_b64 exec, -1
	v_lshl_add_u64 v[0:1], v[68:69], 0, s[0:1]
	s_mov_b32 m0, s29
	s_mov_b64 s[0:1], 0x80
	v_readfirstlane_b32 s33, v120
	v_add_u32_e32 v121, 0x14400, v5
	s_mov_b64 exec, vcc
	global_load_lds_dwordx4 v[0:1], off
	s_mov_b64 exec, -1
	v_lshl_add_u64 v[0:1], v[70:71], 0, s[0:1]
	s_mov_b32 m0, s33
	v_readfirstlane_b32 s34, v121
	v_lshrrev_b32_e32 v2, 1, v74
	v_bfe_u32 v64, v74, 5, 1
	global_load_lds_dwordx4 v[0:1], off
	v_lshl_add_u64 v[0:1], v[72:73], 0, s[0:1]
	s_mov_b32 m0, s34
	s_mov_b64 s[0:1], 0x2000100
	global_load_lds_dwordx4 v[0:1], off
	v_bitop3_b32 v0, v2, v64, 7 bitop3:0x6c
	v_add_u32_e32 v110, s3, v3
	v_lshlrev_b32_e32 v128, 4, v0
	s_waitcnt vmcnt(6)
	v_lshl_add_u64 v[0:1], v[66:67], 0, s[0:1]
	v_readfirstlane_b32 s0, v110
	v_add_u32_e32 v111, 0x400, v110
	s_waitcnt lgkmcnt(0)
	s_barrier
	s_mov_b32 m0, s0
	s_mov_b64 s[20:21], 0x2004100
	v_readfirstlane_b32 s1, v111
	v_add_u32_e32 v112, 0x800, v110
	s_mov_b64 exec, vcc
	global_load_lds_dwordx4 v[0:1], off
	s_mov_b64 exec, -1
	v_lshl_add_u64 v[0:1], v[68:69], 0, s[20:21]
	s_mov_b32 m0, s1
	s_mov_b64 s[20:21], 0x2008100
	v_readfirstlane_b32 s2, v112
	s_mov_b64 exec, vcc
	global_load_lds_dwordx4 v[0:1], off
	s_mov_b64 exec, -1
	v_lshl_add_u64 v[0:1], v[66:67], 0, s[20:21]
	s_mov_b32 m0, s2
	s_mov_b64 s[20:21], 0x200c100
	s_mov_b64 exec, vcc
	global_load_lds_dwordx4 v[0:1], off
	s_mov_b64 exec, -1
	v_lshl_add_u64 v[0:1], v[68:69], 0, s[20:21]
	v_add_u32_e32 v113, 0xc00, v110
	v_readlane_b32 s21, v212, 31
	v_and_b32_e32 v75, 31, v74
	v_readfirstlane_b32 s20, v113
	v_add_u32_e32 v114, s21, v4
	v_add_u32_e32 v2, s3, v4
	v_and_b32_e32 v76, 1, v12
	v_lshlrev_b32_e32 v13, 7, v75
	s_mov_b32 m0, s20
	s_mov_b64 s[30:31], 0x100
	v_readfirstlane_b32 s21, v114
	v_add_u32_e32 v115, 0x8400, v2
	v_lshl_or_b32 v98, v76, 13, v13
	s_mov_b64 exec, vcc
	global_load_lds_dwordx4 v[0:1], off
	s_mov_b64 exec, -1
	v_lshl_add_u64 v[0:1], v[70:71], 0, s[30:31]
	s_mov_b32 m0, s21
	v_readfirstlane_b32 s22, v115
	global_load_lds_dwordx4 v[0:1], off
	v_lshl_add_u64 v[0:1], v[72:73], 0, s[30:31]
	s_mov_b32 m0, s22
	v_add_u32_e32 v96, 0, v98
	global_load_lds_dwordx4 v[0:1], off
	v_add_u32_e32 v79, v96, v128
	v_ashrrev_i32_e32 v77, 7, v74
	ds_read_b128 a[0:3], v79 offset:32768
	ds_read_b128 a[4:7], v79 offset:36864
	v_lshl_or_b32 v129, v77, 13, v13
	v_add_u32_e32 v97, 0, v129
	v_add_u32_e32 v78, v97, v128
	ds_read_b128 a[8:11], v78
	ds_read_b128 a[12:15], v78 offset:4096
	s_waitcnt lgkmcnt(1)
	v_mfma_f32_32x32x16_bf16 v[48:63], a[0:3], a[8:11], 0
	v_bfe_u32 v99, v74, 1, 3
	s_mov_b64 s[30:31], 0x2000180
	s_mov_b32 m0, s38
	v_or_b32_e32 v139, 0x8000, v98
	v_or_b32_e32 v140, 0x9000, v98
	v_add_u32_e32 v141, s3, v129
	v_or_b32_e32 v142, 0x1000, v129
	v_mfma_f32_32x32x16_bf16 v[32:47], a[4:7], a[8:11], 0
	v_lshl_or_b32 v77, v77, 6, v75
	v_mul_lo_u32 v77, v77, s26
	s_mov_b64 s[80:81], 0x200
	s_waitcnt lgkmcnt(0)
	v_mfma_f32_32x32x16_bf16 v[16:31], a[0:3], a[12:15], 0
	v_bitop3_b32 v0, v64, v99, 2 bitop3:0x36
	v_lshlrev_b32_e32 v132, 4, v0
	v_add_u32_e32 v80, v97, v132
	ds_read_b128 a[28:31], v80 offset:4096
	s_nop 0
	s_nop 0
	ds_read_b128 a[24:27], v80
	s_nop 0
	v_add_u32_e32 v81, v96, v132
	ds_read_b128 a[20:23], v81 offset:36864
	s_nop 0
	s_nop 0
	ds_read_b128 a[16:19], v81 offset:32768
	s_nop 0
	s_nop 0
	s_nop 0
	s_nop 0
	s_nop 0
	s_nop 0
	v_mfma_f32_32x32x16_bf16 v[0:15], a[4:7], a[12:15], 0
	s_nop 0
	s_waitcnt lgkmcnt(0)
	v_mfma_f32_32x32x16_bf16 v[48:63], a[16:19], a[24:27], v[48:63]
	v_mfma_f32_32x32x16_bf16 v[32:47], a[20:23], a[24:27], v[32:47]
	v_mfma_f32_32x32x16_bf16 v[16:31], a[16:19], a[28:31], v[16:31]
	v_bitop3_b32 v82, v64, v99, 4 bitop3:0x36
	v_lshlrev_b32_e32 v134, 4, v82
	v_add_u32_e32 v82, v97, v134
	ds_read_b128 a[12:15], v82 offset:4096
	s_nop 0
	s_nop 0
	ds_read_b128 a[8:11], v82
	s_nop 0
	v_add_u32_e32 v83, v96, v134
	ds_read_b128 a[4:7], v83 offset:36864
	s_nop 0
	s_nop 0
	ds_read_b128 a[0:3], v83 offset:32768
	s_nop 0
	s_nop 0
	s_nop 0
	v_mfma_f32_32x32x16_bf16 v[0:15], a[20:23], a[28:31], v[0:15]
	s_nop 0
	s_nop 0
	s_nop 0
	s_nop 0
	s_waitcnt lgkmcnt(0)
	v_mfma_f32_32x32x16_bf16 v[48:63], a[0:3], a[8:11], v[48:63]
	v_mfma_f32_32x32x16_bf16 v[32:47], a[4:7], a[8:11], v[32:47]
	v_mfma_f32_32x32x16_bf16 v[16:31], a[0:3], a[12:15], v[16:31]
	v_bitop3_b32 v84, v64, v99, 6 bitop3:0x36
	v_lshlrev_b32_e32 v138, 4, v84
	v_add_u32_e32 v84, v97, v138
	ds_read_b128 a[28:31], v84 offset:4096
	s_nop 0
	s_nop 0
	ds_read_b128 a[24:27], v84
	s_nop 0
	v_add_u32_e32 v85, v96, v138
	ds_read_b128 a[20:23], v85 offset:36864
	s_nop 0
	s_nop 0
	ds_read_b128 a[16:19], v85 offset:32768
	s_nop 0
	s_nop 0
	s_nop 0
	v_lshlrev_b32_e32 v64, 4, v64
	v_lshl_or_b32 v64, v76, 8, v64
	v_add3_u32 v64, 0, v77, v64
	v_mfma_f32_32x32x16_bf16 v[0:15], a[4:7], a[12:15], v[0:15]
	s_nop 0
	s_nop 0
	s_nop 0
	s_nop 0
	s_waitcnt lgkmcnt(0)
	v_mfma_f32_32x32x16_bf16 v[48:63], a[16:19], a[24:27], v[48:63]
	v_mfma_f32_32x32x16_bf16 v[32:47], a[20:23], a[24:27], v[32:47]
	s_waitcnt vmcnt(6)
	s_waitcnt lgkmcnt(0)
	s_barrier
	ds_read_b128 a[12:15], v78 offset:53248
	ds_read_b128 a[8:11], v78 offset:49152
	v_mfma_f32_32x32x16_bf16 v[16:31], a[16:19], a[28:31], v[16:31]
	v_lshl_add_u64 v[86:87], v[66:67], 0, s[30:31]
	s_mov_b64 s[30:31], 0x2004180
	s_mov_b64 exec, vcc
	global_load_lds_dwordx4 v[86:87], off
	s_mov_b64 exec, -1
	v_lshl_add_u64 v[86:87], v[68:69], 0, s[30:31]
	s_mov_b32 m0, s37
	s_mov_b64 s[30:31], 0x2008180
	s_mov_b64 exec, vcc
	global_load_lds_dwordx4 v[86:87], off
	s_mov_b64 exec, -1
	v_lshl_add_u64 v[86:87], v[66:67], 0, s[30:31]
	s_mov_b32 m0, s36
	s_mov_b64 s[30:31], 0x200c180
	s_mov_b64 exec, vcc
	global_load_lds_dwordx4 v[86:87], off
	s_mov_b64 exec, -1
	v_lshl_add_u64 v[86:87], v[68:69], 0, s[30:31]
	s_mov_b32 m0, s35
	s_mov_b64 s[30:31], 0x180
	s_mov_b64 exec, vcc
	global_load_lds_dwordx4 v[86:87], off
	s_mov_b64 exec, -1
	v_lshl_add_u64 v[86:87], v[70:71], 0, s[30:31]
	s_mov_b32 m0, s39
	v_mfma_f32_32x32x16_bf16 v[0:15], a[20:23], a[28:31], v[0:15]
	global_load_lds_dwordx4 v[86:87], off
	v_lshl_add_u64 v[86:87], v[72:73], 0, s[30:31]
	s_mov_b32 m0, s40
	s_add_i32 s30, 0, 0xc000
	global_load_lds_dwordx4 v[86:87], off
	v_add_u32_e32 v86, s30, v128
	v_add_u32_e32 v88, v86, v139
	v_add_u32_e32 v86, v86, v140
	ds_read_b128 a[4:7], v86
	ds_read_b128 a[0:3], v88
	s_nop 0
	s_nop 0
	s_nop 0
	s_nop 0
	s_nop 0
	s_nop 0
	s_nop 0
	v_add_u32_e32 v87, s30, v132
	v_add_u32_e32 v89, v87, v139
	ds_read_b128 a[16:19], v89
	v_add_u32_e32 v87, v87, v140
	ds_read_b128 a[20:23], v87
	ds_read_b128 a[24:27], v80 offset:49152
	ds_read_b128 a[28:31], v80 offset:53248
	s_waitcnt lgkmcnt(4)
	v_mfma_f32_32x32x16_bf16 v[48:63], a[0:3], a[8:11], v[48:63]
	s_nop 0
	s_nop 0
	s_nop 0
	s_mov_b32 m0, s23
	v_mfma_f32_32x32x16_bf16 v[32:47], a[4:7], a[8:11], v[32:47]
	v_mfma_f32_32x32x16_bf16 v[16:31], a[0:3], a[12:15], v[16:31]
	v_mfma_f32_32x32x16_bf16 v[0:15], a[4:7], a[12:15], v[0:15]
	s_nop 0
	s_nop 0
	s_nop 0
	s_nop 0
	v_add_u32_e32 v90, s30, v134
	v_add_u32_e32 v91, v90, v139
	ds_read_b128 a[0:3], v91
	v_add_u32_e32 v90, v90, v140
	ds_read_b128 a[4:7], v90
	ds_read_b128 a[8:11], v82 offset:49152
	ds_read_b128 a[12:15], v82 offset:53248
	s_waitcnt lgkmcnt(5)
	v_mfma_f32_32x32x16_bf16 v[48:63], a[16:19], a[24:27], v[48:63]
	v_mfma_f32_32x32x16_bf16 v[32:47], a[20:23], a[24:27], v[32:47]
	s_waitcnt lgkmcnt(4)
	v_mfma_f32_32x32x16_bf16 v[16:31], a[16:19], a[28:31], v[16:31]
	s_nop 0
	s_nop 0
	s_nop 0
	v_mfma_f32_32x32x16_bf16 v[0:15], a[20:23], a[28:31], v[0:15]
	s_nop 0
	s_nop 0
	s_nop 0
	s_nop 0
	v_add_u32_e32 v92, s30, v138
	v_add_u32_e32 v93, v92, v139
	ds_read_b128 a[16:19], v93
	v_add_u32_e32 v92, v92, v140
	ds_read_b128 a[20:23], v92
	ds_read_b128 a[24:27], v84 offset:49152
	ds_read_b128 a[28:31], v84 offset:53248
	s_waitcnt lgkmcnt(5)
	v_mfma_f32_32x32x16_bf16 v[48:63], a[0:3], a[8:11], v[48:63]
	v_mfma_f32_32x32x16_bf16 v[32:47], a[4:7], a[8:11], v[32:47]
	s_waitcnt lgkmcnt(4)
	v_mfma_f32_32x32x16_bf16 v[16:31], a[0:3], a[12:15], v[16:31]
	s_nop 0
	s_nop 0
	s_nop 0
	s_mov_b64 s[30:31], 0x2000200
	v_mfma_f32_32x32x16_bf16 v[0:15], a[4:7], a[12:15], v[0:15]
	s_nop 0
	s_nop 0
	s_nop 0
	s_nop 0
	s_waitcnt lgkmcnt(1)
	v_mfma_f32_32x32x16_bf16 v[48:63], a[16:19], a[24:27], v[48:63]
	v_mfma_f32_32x32x16_bf16 v[32:47], a[20:23], a[24:27], v[32:47]
	s_waitcnt vmcnt(6)
	s_waitcnt lgkmcnt(0)
	s_barrier
	v_add_u32_e32 v96, v141, v128
	ds_read_b128 a[8:11], v96
	v_mfma_f32_32x32x16_bf16 v[16:31], a[16:19], a[28:31], v[16:31]
	v_lshl_add_u64 v[94:95], v[66:67], 0, s[30:31]
	s_mov_b64 s[30:31], 0x2004200
	s_mov_b64 exec, vcc
	global_load_lds_dwordx4 v[94:95], off
	s_mov_b64 exec, -1
	v_lshl_add_u64 v[94:95], v[68:69], 0, s[30:31]
	s_mov_b32 m0, s24
	s_mov_b64 s[30:31], 0x2008200
	s_mov_b64 exec, vcc
	global_load_lds_dwordx4 v[94:95], off
	s_mov_b64 exec, -1
	v_lshl_add_u64 v[94:95], v[66:67], 0, s[30:31]
	s_mov_b32 m0, s28
	s_mov_b64 s[30:31], 0x200c200
	s_mov_b64 exec, vcc
	global_load_lds_dwordx4 v[94:95], off
	s_mov_b64 exec, -1
	v_lshl_add_u64 v[94:95], v[68:69], 0, s[30:31]
	s_mov_b32 m0, s29
	s_mov_b64 s[30:31], 0x200
	s_mov_b64 exec, vcc
	global_load_lds_dwordx4 v[94:95], off
	s_mov_b64 exec, -1
	v_lshl_add_u64 v[94:95], v[70:71], 0, s[30:31]
	s_mov_b32 m0, s33
	v_add_u32_e32 v97, s3, v128
	global_load_lds_dwordx4 v[94:95], off
	v_lshl_add_u64 v[94:95], v[72:73], 0, s[30:31]
	s_mov_b32 m0, s34
	v_mfma_f32_32x32x16_bf16 v[0:15], a[20:23], a[28:31], v[0:15]
	global_load_lds_dwordx4 v[94:95], off
	v_add_u32_e32 v95, v97, v140
	ds_read_b128 a[4:7], v95
	v_add_u32_e32 v94, v97, v139
	v_add_u32_e32 v97, v97, v142
	ds_read_b128 a[12:15], v97
	ds_read_b128 a[0:3], v94
	s_nop 0
	s_nop 0
	s_nop 0
	s_nop 0
	s_nop 0
	s_nop 0
	s_nop 0
	s_nop 0
	v_add_u32_e32 v101, s3, v132
	v_add_u32_e32 v98, v101, v139
	ds_read_b128 a[16:19], v98
	v_add_u32_e32 v99, v101, v140
	ds_read_b128 a[20:23], v99
	v_add_u32_e32 v100, v141, v132
	ds_read_b128 a[24:27], v100
	v_add_u32_e32 v101, v101, v142
	ds_read_b128 a[28:31], v101
	s_waitcnt lgkmcnt(4)
	v_mfma_f32_32x32x16_bf16 v[48:63], a[0:3], a[8:11], v[48:63]
	s_mov_b64 s[30:31], 0x2000280
	s_mov_b32 m0, s0
	v_mfma_f32_32x32x16_bf16 v[32:47], a[4:7], a[8:11], v[32:47]
	s_nop 0
	s_nop 0
	s_nop 0
	s_nop 0
	s_nop 0
	v_mfma_f32_32x32x16_bf16 v[16:31], a[0:3], a[12:15], v[16:31]
	s_nop 0
	v_mfma_f32_32x32x16_bf16 v[0:15], a[4:7], a[12:15], v[0:15]
	s_nop 0
	s_nop 0
	s_nop 0
	v_add_u32_e32 v105, s3, v134
	v_add_u32_e32 v102, v105, v139
	ds_read_b128 a[0:3], v102
	v_add_u32_e32 v103, v105, v140
	ds_read_b128 a[4:7], v103
	v_add_u32_e32 v104, v141, v134
	ds_read_b128 a[8:11], v104
	v_add_u32_e32 v105, v105, v142
	ds_read_b128 a[12:15], v105
	s_waitcnt lgkmcnt(5)
	v_mfma_f32_32x32x16_bf16 v[48:63], a[16:19], a[24:27], v[48:63]
	v_mfma_f32_32x32x16_bf16 v[32:47], a[20:23], a[24:27], v[32:47]
	s_waitcnt lgkmcnt(4)
	v_mfma_f32_32x32x16_bf16 v[16:31], a[16:19], a[28:31], v[16:31]
	s_nop 0
	s_nop 0
	s_nop 0
	s_nop 0
	s_nop 0
	s_nop 0
	v_mfma_f32_32x32x16_bf16 v[0:15], a[20:23], a[28:31], v[0:15]
	s_nop 0
	s_nop 0
	s_nop 0
	v_add_u32_e32 v109, s3, v138
	v_add_u32_e32 v106, v109, v139
	ds_read_b128 a[16:19], v106
	v_add_u32_e32 v107, v109, v140
	ds_read_b128 a[20:23], v107
	v_add_u32_e32 v108, v141, v138
	ds_read_b128 a[24:27], v108
	v_add_u32_e32 v109, v109, v142
	ds_read_b128 a[28:31], v109
	s_waitcnt lgkmcnt(5)
	v_mfma_f32_32x32x16_bf16 v[48:63], a[0:3], a[8:11], v[48:63]
	v_mfma_f32_32x32x16_bf16 v[32:47], a[4:7], a[8:11], v[32:47]
	s_waitcnt lgkmcnt(4)
	v_mfma_f32_32x32x16_bf16 v[16:31], a[0:3], a[12:15], v[16:31]
	s_nop 0
	s_nop 0
	s_nop 0
	s_nop 0
	s_nop 0
	s_nop 0
	v_mfma_f32_32x32x16_bf16 v[0:15], a[4:7], a[12:15], v[0:15]
	s_nop 0
	s_nop 0
	s_nop 0
	s_waitcnt lgkmcnt(1)
	v_mfma_f32_32x32x16_bf16 v[48:63], a[16:19], a[24:27], v[48:63]
	v_mfma_f32_32x32x16_bf16 v[32:47], a[20:23], a[24:27], v[32:47]
	s_waitcnt vmcnt(6)
	s_waitcnt lgkmcnt(0)
	s_barrier
	ds_read_b128 a[12:15], v78 offset:4096
	ds_read_b128 a[8:11], v78
	ds_read_b128 a[4:7], v79 offset:36864
	ds_read_b128 a[0:3], v79 offset:32768
	v_mfma_f32_32x32x16_bf16 v[16:31], a[16:19], a[28:31], v[16:31]
	v_lshl_add_u64 v[128:129], v[66:67], 0, s[30:31]
	s_mov_b64 s[30:31], 0x2004280
	s_mov_b64 exec, vcc
	global_load_lds_dwordx4 v[128:129], off
	s_mov_b64 exec, -1
	v_lshl_add_u64 v[128:129], v[68:69], 0, s[30:31]
	s_mov_b32 m0, s1
	s_mov_b64 s[30:31], 0x2008280
	s_mov_b64 exec, vcc
	global_load_lds_dwordx4 v[128:129], off
	s_mov_b64 exec, -1
	v_lshl_add_u64 v[128:129], v[66:67], 0, s[30:31]
	s_mov_b32 m0, s2
	s_mov_b64 s[30:31], 0x200c280
	s_mov_b64 exec, vcc
	global_load_lds_dwordx4 v[128:129], off
	s_mov_b64 exec, -1
	v_lshl_add_u64 v[128:129], v[68:69], 0, s[30:31]
	s_mov_b32 m0, s20
	s_mov_b64 s[30:31], 0x280
	s_mov_b64 exec, vcc
	global_load_lds_dwordx4 v[128:129], off
	s_mov_b64 exec, -1
	v_lshl_add_u64 v[128:129], v[70:71], 0, s[30:31]
	s_mov_b32 m0, s21
	v_mfma_f32_32x32x16_bf16 v[0:15], a[20:23], a[28:31], v[0:15]
	global_load_lds_dwordx4 v[128:129], off
	v_lshl_add_u64 v[128:129], v[72:73], 0, s[30:31]
	s_mov_b32 m0, s22
	s_mov_b64 s[30:31], 0x2000300
	global_load_lds_dwordx4 v[128:129], off
	s_nop 0
	s_nop 0
	s_nop 0
	s_nop 0
	ds_read_b128 a[16:19], v81 offset:32768
	ds_read_b128 a[20:23], v81 offset:36864
	ds_read_b128 a[24:27], v80
	ds_read_b128 a[28:31], v80 offset:4096
	s_waitcnt lgkmcnt(4)
	v_mfma_f32_32x32x16_bf16 v[48:63], a[0:3], a[8:11], v[48:63]
	s_mov_b32 m0, s38
	v_readfirstlane_b32 s38, v113
	v_mfma_f32_32x32x16_bf16 v[32:47], a[4:7], a[8:11], v[32:47]
	v_mfma_f32_32x32x16_bf16 v[16:31], a[0:3], a[12:15], v[16:31]
	v_mfma_f32_32x32x16_bf16 v[0:15], a[4:7], a[12:15], v[0:15]
	s_nop 0
	s_nop 0
	s_nop 0
	s_nop 0
	ds_read_b128 a[0:3], v83 offset:32768
	ds_read_b128 a[4:7], v83 offset:36864
	ds_read_b128 a[8:11], v82
	ds_read_b128 a[12:15], v82 offset:4096
	s_waitcnt lgkmcnt(5)
	v_mfma_f32_32x32x16_bf16 v[48:63], a[16:19], a[24:27], v[48:63]
	v_mfma_f32_32x32x16_bf16 v[32:47], a[20:23], a[24:27], v[32:47]
	s_waitcnt lgkmcnt(4)
	v_mfma_f32_32x32x16_bf16 v[16:31], a[16:19], a[28:31], v[16:31]
	v_mfma_f32_32x32x16_bf16 v[0:15], a[20:23], a[28:31], v[0:15]
	s_nop 0
	s_nop 0
	s_nop 0
	s_nop 0
	ds_read_b128 a[16:19], v85 offset:32768
	ds_read_b128 a[20:23], v85 offset:36864
	ds_read_b128 a[24:27], v84
	ds_read_b128 a[28:31], v84 offset:4096
	s_waitcnt lgkmcnt(5)
	v_mfma_f32_32x32x16_bf16 v[48:63], a[0:3], a[8:11], v[48:63]
	v_mfma_f32_32x32x16_bf16 v[32:47], a[4:7], a[8:11], v[32:47]
	s_waitcnt lgkmcnt(4)
	v_mfma_f32_32x32x16_bf16 v[16:31], a[0:3], a[12:15], v[16:31]
	v_mfma_f32_32x32x16_bf16 v[0:15], a[4:7], a[12:15], v[0:15]
	s_nop 0
	s_nop 0
	s_nop 0
	s_nop 0
	s_waitcnt lgkmcnt(1)
	v_mfma_f32_32x32x16_bf16 v[48:63], a[16:19], a[24:27], v[48:63]
	v_mfma_f32_32x32x16_bf16 v[32:47], a[20:23], a[24:27], v[32:47]
	s_waitcnt vmcnt(6)
	s_waitcnt lgkmcnt(0)
	s_barrier
	ds_read_b128 a[12:15], v78 offset:53248
	ds_read_b128 a[8:11], v78 offset:49152
	ds_read_b128 a[4:7], v86
	ds_read_b128 a[0:3], v88
	v_mfma_f32_32x32x16_bf16 v[16:31], a[16:19], a[28:31], v[16:31]
	v_lshl_add_u64 v[128:129], v[66:67], 0, s[30:31]
	s_mov_b64 s[30:31], 0x2004300
	s_mov_b64 exec, vcc
	global_load_lds_dwordx4 v[128:129], off
	s_mov_b64 exec, -1
	v_lshl_add_u64 v[128:129], v[68:69], 0, s[30:31]
	s_mov_b32 m0, s37
	s_mov_b64 s[30:31], 0x2008300
	s_mov_b64 exec, vcc
	global_load_lds_dwordx4 v[128:129], off
	s_mov_b64 exec, -1
	v_lshl_add_u64 v[128:129], v[66:67], 0, s[30:31]
	s_mov_b32 m0, s36
	s_mov_b64 s[30:31], 0x200c300
	s_mov_b64 exec, vcc
	global_load_lds_dwordx4 v[128:129], off
	s_mov_b64 exec, -1
	v_lshl_add_u64 v[128:129], v[68:69], 0, s[30:31]
	s_mov_b32 m0, s35
	s_mov_b64 s[30:31], 0x300
	s_mov_b64 exec, vcc
	global_load_lds_dwordx4 v[128:129], off
	s_mov_b64 exec, -1
	v_lshl_add_u64 v[128:129], v[70:71], 0, s[30:31]
	s_mov_b32 m0, s39
	v_mfma_f32_32x32x16_bf16 v[0:15], a[20:23], a[28:31], v[0:15]
	global_load_lds_dwordx4 v[128:129], off
	v_lshl_add_u64 v[128:129], v[72:73], 0, s[30:31]
	s_mov_b32 m0, s40
	s_mov_b64 s[30:31], 0x2000380
	global_load_lds_dwordx4 v[128:129], off
	s_nop 0
	s_nop 0
	s_nop 0
	s_nop 0
	ds_read_b128 a[16:19], v89
	ds_read_b128 a[20:23], v87
	ds_read_b128 a[24:27], v80 offset:49152
	ds_read_b128 a[28:31], v80 offset:53248
	s_waitcnt lgkmcnt(4)
	v_mfma_f32_32x32x16_bf16 v[48:63], a[0:3], a[8:11], v[48:63]
	s_mov_b32 m0, s23
	v_readfirstlane_b32 s35, v110
	v_readfirstlane_b32 s36, v111
	v_readfirstlane_b32 s37, v112
	v_readfirstlane_b32 s39, v114
	v_readfirstlane_b32 s40, v115
	v_mfma_f32_32x32x16_bf16 v[32:47], a[4:7], a[8:11], v[32:47]
	v_mfma_f32_32x32x16_bf16 v[16:31], a[0:3], a[12:15], v[16:31]
	v_mfma_f32_32x32x16_bf16 v[0:15], a[4:7], a[12:15], v[0:15]
	s_nop 0
	s_nop 0
	s_nop 0
	s_nop 0
	ds_read_b128 a[0:3], v91
	ds_read_b128 a[4:7], v90
	ds_read_b128 a[8:11], v82 offset:49152
	ds_read_b128 a[12:15], v82 offset:53248
	s_waitcnt lgkmcnt(5)
	v_mfma_f32_32x32x16_bf16 v[48:63], a[16:19], a[24:27], v[48:63]
	v_mfma_f32_32x32x16_bf16 v[32:47], a[20:23], a[24:27], v[32:47]
	s_waitcnt lgkmcnt(4)
	v_mfma_f32_32x32x16_bf16 v[16:31], a[16:19], a[28:31], v[16:31]
	v_mfma_f32_32x32x16_bf16 v[0:15], a[20:23], a[28:31], v[0:15]
	s_nop 0
	s_nop 0
	s_nop 0
	s_nop 0
	ds_read_b128 a[16:19], v93
	ds_read_b128 a[20:23], v92
	ds_read_b128 a[24:27], v84 offset:49152
	ds_read_b128 a[28:31], v84 offset:53248
	s_waitcnt lgkmcnt(5)
	v_mfma_f32_32x32x16_bf16 v[48:63], a[0:3], a[8:11], v[48:63]
	v_mfma_f32_32x32x16_bf16 v[32:47], a[4:7], a[8:11], v[32:47]
	s_waitcnt lgkmcnt(4)
	v_mfma_f32_32x32x16_bf16 v[16:31], a[0:3], a[12:15], v[16:31]
	v_mfma_f32_32x32x16_bf16 v[0:15], a[4:7], a[12:15], v[0:15]
	s_nop 0
	s_nop 0
	s_nop 0
	s_nop 0
	s_waitcnt lgkmcnt(1)
	v_mfma_f32_32x32x16_bf16 v[48:63], a[16:19], a[24:27], v[48:63]
	v_mfma_f32_32x32x16_bf16 v[32:47], a[20:23], a[24:27], v[32:47]
	s_waitcnt vmcnt(6)
	s_waitcnt lgkmcnt(0)
	s_barrier
	ds_read_b128 a[12:15], v97
	ds_read_b128 a[8:11], v96
	ds_read_b128 a[4:7], v95
	ds_read_b128 a[0:3], v94
	v_mfma_f32_32x32x16_bf16 v[16:31], a[16:19], a[28:31], v[16:31]
	v_lshl_add_u64 v[128:129], v[66:67], 0, s[30:31]
	s_mov_b64 s[30:31], 0x2004380
	s_mov_b64 exec, vcc
	global_load_lds_dwordx4 v[128:129], off
	s_mov_b64 exec, -1
	v_lshl_add_u64 v[128:129], v[68:69], 0, s[30:31]
	s_mov_b32 m0, s24
	s_mov_b64 s[30:31], 0x2008380
	s_mov_b64 exec, vcc
	global_load_lds_dwordx4 v[128:129], off
	s_mov_b64 exec, -1
	v_lshl_add_u64 v[128:129], v[66:67], 0, s[30:31]
	s_mov_b32 m0, s28
	s_mov_b64 s[30:31], 0x200c380
	s_mov_b64 exec, vcc
	global_load_lds_dwordx4 v[128:129], off
	s_mov_b64 exec, -1
	v_lshl_add_u64 v[128:129], v[68:69], 0, s[30:31]
	s_mov_b32 m0, s29
	s_mov_b64 s[28:29], 0x380
	s_mov_b64 exec, vcc
	global_load_lds_dwordx4 v[128:129], off
	s_mov_b64 exec, -1
	v_lshl_add_u64 v[128:129], v[70:71], 0, s[28:29]
	s_mov_b32 m0, s33
	v_mfma_f32_32x32x16_bf16 v[0:15], a[20:23], a[28:31], v[0:15]
	global_load_lds_dwordx4 v[128:129], off
	v_lshl_add_u64 v[128:129], v[72:73], 0, s[28:29]
	s_mov_b32 m0, s34
	s_mov_b64 s[28:29], 0x2000400
	global_load_lds_dwordx4 v[128:129], off
	s_nop 0
	s_nop 0
	s_nop 0
	s_nop 0
	ds_read_b128 a[16:19], v98
	ds_read_b128 a[20:23], v99
	ds_read_b128 a[24:27], v100
	ds_read_b128 a[28:31], v101
	s_waitcnt lgkmcnt(4)
	v_mfma_f32_32x32x16_bf16 v[48:63], a[0:3], a[8:11], v[48:63]
	s_mov_b32 m0, s0
	v_readfirstlane_b32 s24, v117
	s_mov_b64 s[30:31], 0x200c500
	v_readfirstlane_b32 s33, v120
	v_readfirstlane_b32 s34, v121
	v_mfma_f32_32x32x16_bf16 v[32:47], a[4:7], a[8:11], v[32:47]
	v_mfma_f32_32x32x16_bf16 v[16:31], a[0:3], a[12:15], v[16:31]
	v_mfma_f32_32x32x16_bf16 v[0:15], a[4:7], a[12:15], v[0:15]
	s_nop 0
	s_nop 0
	s_nop 0
	s_nop 0
	ds_read_b128 a[0:3], v102
	ds_read_b128 a[4:7], v103
	ds_read_b128 a[8:11], v104
	ds_read_b128 a[12:15], v105
	s_waitcnt lgkmcnt(5)
	v_mfma_f32_32x32x16_bf16 v[48:63], a[16:19], a[24:27], v[48:63]
	v_mfma_f32_32x32x16_bf16 v[32:47], a[20:23], a[24:27], v[32:47]
	s_waitcnt lgkmcnt(4)
	v_mfma_f32_32x32x16_bf16 v[16:31], a[16:19], a[28:31], v[16:31]
	v_mfma_f32_32x32x16_bf16 v[0:15], a[20:23], a[28:31], v[0:15]
	s_nop 0
	s_nop 0
	s_nop 0
	s_nop 0
	ds_read_b128 a[16:19], v106
	ds_read_b128 a[20:23], v107
	ds_read_b128 a[24:27], v108
	ds_read_b128 a[28:31], v109
	s_waitcnt lgkmcnt(5)
	v_mfma_f32_32x32x16_bf16 v[48:63], a[0:3], a[8:11], v[48:63]
	v_mfma_f32_32x32x16_bf16 v[32:47], a[4:7], a[8:11], v[32:47]
	s_waitcnt lgkmcnt(4)
	v_mfma_f32_32x32x16_bf16 v[16:31], a[0:3], a[12:15], v[16:31]
	v_mfma_f32_32x32x16_bf16 v[0:15], a[4:7], a[12:15], v[0:15]
	s_nop 0
	s_nop 0
	s_nop 0
	s_nop 0
	s_waitcnt lgkmcnt(1)
	v_mfma_f32_32x32x16_bf16 v[48:63], a[16:19], a[24:27], v[48:63]
	v_mfma_f32_32x32x16_bf16 v[32:47], a[20:23], a[24:27], v[32:47]
	s_waitcnt vmcnt(6)
	s_waitcnt lgkmcnt(0)
	s_barrier
	ds_read_b128 a[12:15], v78 offset:4096
	ds_read_b128 a[8:11], v78
	ds_read_b128 a[4:7], v79 offset:36864
	ds_read_b128 a[0:3], v79 offset:32768
	v_mfma_f32_32x32x16_bf16 v[16:31], a[16:19], a[28:31], v[16:31]
	v_lshl_add_u64 v[128:129], v[66:67], 0, s[28:29]
	s_mov_b64 s[28:29], 0x2004400
	s_mov_b64 exec, vcc
	global_load_lds_dwordx4 v[128:129], off
	s_mov_b64 exec, -1
	v_lshl_add_u64 v[128:129], v[68:69], 0, s[28:29]
	s_mov_b32 m0, s1
	s_mov_b64 s[0:1], 0x2008400
	s_mov_b64 exec, vcc
	global_load_lds_dwordx4 v[128:129], off
	s_mov_b64 exec, -1
	v_lshl_add_u64 v[128:129], v[66:67], 0, s[0:1]
	s_mov_b32 m0, s2
	s_mov_b64 s[0:1], 0x200c400
	s_mov_b64 exec, vcc
	global_load_lds_dwordx4 v[128:129], off
	s_mov_b64 exec, -1
	v_lshl_add_u64 v[128:129], v[68:69], 0, s[0:1]
	s_mov_b32 m0, s20
	s_mov_b64 s[0:1], 0x400
	s_mov_b64 exec, vcc
	global_load_lds_dwordx4 v[128:129], off
	s_mov_b64 exec, -1
	v_lshl_add_u64 v[128:129], v[70:71], 0, s[0:1]
	s_mov_b32 m0, s21
	v_mfma_f32_32x32x16_bf16 v[0:15], a[20:23], a[28:31], v[0:15]
	global_load_lds_dwordx4 v[128:129], off
	v_lshl_add_u64 v[128:129], v[72:73], 0, s[0:1]
	s_mov_b32 m0, s22
	s_mov_b64 s[0:1], 0x2000480
	global_load_lds_dwordx4 v[128:129], off
	s_nop 0
	s_nop 0
	s_nop 0
	s_nop 0
	ds_read_b128 a[16:19], v81 offset:32768
	ds_read_b128 a[20:23], v81 offset:36864
	ds_read_b128 a[24:27], v80
	ds_read_b128 a[28:31], v80 offset:4096
	s_waitcnt lgkmcnt(4)
	v_mfma_f32_32x32x16_bf16 v[48:63], a[0:3], a[8:11], v[48:63]
	s_mov_b64 s[20:21], 0x2004480
	v_readfirstlane_b32 s2, v124
	s_mov_b64 s[22:23], 0x480
	s_mov_b64 s[28:29], 0x2000500
	v_mfma_f32_32x32x16_bf16 v[32:47], a[4:7], a[8:11], v[32:47]
	v_mfma_f32_32x32x16_bf16 v[16:31], a[0:3], a[12:15], v[16:31]
	v_mfma_f32_32x32x16_bf16 v[0:15], a[4:7], a[12:15], v[0:15]
	s_nop 0
	s_nop 0
	s_nop 0
	s_nop 0
	ds_read_b128 a[0:3], v83 offset:32768
	ds_read_b128 a[4:7], v83 offset:36864
	ds_read_b128 a[8:11], v82
	ds_read_b128 a[12:15], v82 offset:4096
	s_waitcnt lgkmcnt(5)
	v_mfma_f32_32x32x16_bf16 v[48:63], a[16:19], a[24:27], v[48:63]
	v_mfma_f32_32x32x16_bf16 v[32:47], a[20:23], a[24:27], v[32:47]
	s_waitcnt lgkmcnt(4)
	v_mfma_f32_32x32x16_bf16 v[16:31], a[16:19], a[28:31], v[16:31]
	v_mfma_f32_32x32x16_bf16 v[0:15], a[20:23], a[28:31], v[0:15]
	s_nop 0
	s_nop 0
	s_nop 0
	s_nop 0
	ds_read_b128 a[16:19], v85 offset:32768
	ds_read_b128 a[20:23], v85 offset:36864
	ds_read_b128 a[24:27], v84
	ds_read_b128 a[28:31], v84 offset:4096
	s_waitcnt lgkmcnt(5)
	v_mfma_f32_32x32x16_bf16 v[48:63], a[0:3], a[8:11], v[48:63]
	v_mfma_f32_32x32x16_bf16 v[32:47], a[4:7], a[8:11], v[32:47]
	s_waitcnt lgkmcnt(4)
	v_mfma_f32_32x32x16_bf16 v[16:31], a[0:3], a[12:15], v[16:31]
	v_mfma_f32_32x32x16_bf16 v[0:15], a[4:7], a[12:15], v[0:15]
	s_nop 0
	s_nop 0
	s_nop 0
	s_nop 0
	s_waitcnt lgkmcnt(1)
	v_mfma_f32_32x32x16_bf16 v[48:63], a[16:19], a[24:27], v[48:63]
	v_mfma_f32_32x32x16_bf16 v[32:47], a[20:23], a[24:27], v[32:47]
	s_waitcnt vmcnt(6)
	s_waitcnt lgkmcnt(0)
	s_barrier
	ds_read_b128 a[12:15], v78 offset:53248
	ds_read_b128 a[8:11], v78 offset:49152
	ds_read_b128 a[4:7], v86
	ds_read_b128 a[0:3], v88
	v_mfma_f32_32x32x16_bf16 v[16:31], a[16:19], a[28:31], v[16:31]
	v_lshl_add_u64 v[128:129], v[66:67], 0, s[0:1]
	v_readfirstlane_b32 s0, v127
	s_mov_b32 m0, s0
	v_readfirstlane_b32 s1, v126
	s_mov_b64 exec, vcc
	global_load_lds_dwordx4 v[128:129], off
	s_mov_b64 exec, -1
	v_lshl_add_u64 v[128:129], v[68:69], 0, s[20:21]
	s_mov_b32 m0, s1
	s_mov_b64 s[20:21], 0x2008480
	s_mov_b64 exec, vcc
	global_load_lds_dwordx4 v[128:129], off
	s_mov_b64 exec, -1
	v_lshl_add_u64 v[126:127], v[66:67], 0, s[20:21]
	s_mov_b32 m0, s2
	s_mov_b64 s[20:21], 0x200c480
	s_mov_b64 exec, vcc
	global_load_lds_dwordx4 v[126:127], off
	s_mov_b64 exec, -1
	v_lshl_add_u64 v[126:127], v[68:69], 0, s[20:21]
	v_readfirstlane_b32 s20, v122
	s_mov_b32 m0, s20
	v_readfirstlane_b32 s21, v125
	s_mov_b64 exec, vcc
	global_load_lds_dwordx4 v[126:127], off
	s_mov_b64 exec, -1
	v_lshl_add_u64 v[126:127], v[70:71], 0, s[22:23]
	s_mov_b32 m0, s21
	v_lshl_add_u64 v[124:125], v[72:73], 0, s[22:23]
	v_readfirstlane_b32 s22, v123
	global_load_lds_dwordx4 v[126:127], off
	s_mov_b32 m0, s22
	v_mfma_f32_32x32x16_bf16 v[0:15], a[20:23], a[28:31], v[0:15]
	global_load_lds_dwordx4 v[124:125], off
	s_nop 0
	s_nop 0
	s_nop 0
	v_readfirstlane_b32 s23, v116
	s_mov_b32 m0, s23
	s_nop 0
	ds_read_b128 a[16:19], v89
	ds_read_b128 a[20:23], v87
	ds_read_b128 a[24:27], v80 offset:49152
	ds_read_b128 a[28:31], v80 offset:53248
	s_waitcnt lgkmcnt(4)
	v_mfma_f32_32x32x16_bf16 v[48:63], a[0:3], a[8:11], v[48:63]
	v_mfma_f32_32x32x16_bf16 v[32:47], a[4:7], a[8:11], v[32:47]
	v_mfma_f32_32x32x16_bf16 v[16:31], a[0:3], a[12:15], v[16:31]
	v_mfma_f32_32x32x16_bf16 v[0:15], a[4:7], a[12:15], v[0:15]
	s_nop 0
	s_nop 0
	s_nop 0
	s_nop 0
	ds_read_b128 a[0:3], v91
	ds_read_b128 a[4:7], v90
	ds_read_b128 a[8:11], v82 offset:49152
	ds_read_b128 a[12:15], v82 offset:53248
	s_waitcnt lgkmcnt(5)
	v_mfma_f32_32x32x16_bf16 v[48:63], a[16:19], a[24:27], v[48:63]
	v_mfma_f32_32x32x16_bf16 v[32:47], a[20:23], a[24:27], v[32:47]
	s_waitcnt lgkmcnt(4)
	v_mfma_f32_32x32x16_bf16 v[16:31], a[16:19], a[28:31], v[16:31]
	v_mfma_f32_32x32x16_bf16 v[0:15], a[20:23], a[28:31], v[0:15]
	s_nop 0
	s_nop 0
	s_nop 0
	s_nop 0
	ds_read_b128 a[16:19], v93
	ds_read_b128 a[20:23], v92
	ds_read_b128 a[24:27], v84 offset:49152
	ds_read_b128 a[28:31], v84 offset:53248
	s_waitcnt lgkmcnt(5)
	v_mfma_f32_32x32x16_bf16 v[48:63], a[0:3], a[8:11], v[48:63]
	v_mfma_f32_32x32x16_bf16 v[32:47], a[4:7], a[8:11], v[32:47]
	s_waitcnt lgkmcnt(4)
	v_mfma_f32_32x32x16_bf16 v[16:31], a[0:3], a[12:15], v[16:31]
	v_mfma_f32_32x32x16_bf16 v[0:15], a[4:7], a[12:15], v[0:15]
	s_nop 0
	s_nop 0
	s_nop 0
	s_nop 0
	s_waitcnt lgkmcnt(1)
	v_mfma_f32_32x32x16_bf16 v[48:63], a[16:19], a[24:27], v[48:63]
	v_mfma_f32_32x32x16_bf16 v[32:47], a[20:23], a[24:27], v[32:47]
	s_waitcnt vmcnt(6)
	s_waitcnt lgkmcnt(0)
	s_barrier
	ds_read_b128 a[12:15], v97
	ds_read_b128 a[8:11], v96
	ds_read_b128 a[4:7], v95
	ds_read_b128 a[0:3], v94
	v_mfma_f32_32x32x16_bf16 v[16:31], a[16:19], a[28:31], v[16:31]
	v_lshl_add_u64 v[122:123], v[66:67], 0, s[28:29]
	s_mov_b64 s[28:29], 0x2004500
	s_mov_b64 exec, vcc
	global_load_lds_dwordx4 v[122:123], off
	s_mov_b64 exec, -1
	v_lshl_add_u64 v[122:123], v[68:69], 0, s[28:29]
	s_mov_b64 s[28:29], 0x2008500
	s_mov_b32 m0, s24
	v_lshl_add_u64 v[116:117], v[66:67], 0, s[28:29]
	v_readfirstlane_b32 s28, v118
	s_mov_b64 exec, vcc
	global_load_lds_dwordx4 v[122:123], off
	s_mov_b64 exec, -1
	s_mov_b32 m0, s28
	v_readfirstlane_b32 s29, v119
	s_mov_b64 exec, vcc
	global_load_lds_dwordx4 v[116:117], off
	s_mov_b64 exec, -1
	v_lshl_add_u64 v[116:117], v[68:69], 0, s[30:31]
	s_mov_b32 m0, s29
	s_mov_b64 s[30:31], 0x500
	s_mov_b64 exec, vcc
	global_load_lds_dwordx4 v[116:117], off
	s_mov_b64 exec, -1
	v_lshl_add_u64 v[116:117], v[70:71], 0, s[30:31]
	s_mov_b32 m0, s33
	v_mfma_f32_32x32x16_bf16 v[0:15], a[20:23], a[28:31], v[0:15]
	global_load_lds_dwordx4 v[116:117], off
	v_lshl_add_u64 v[116:117], v[72:73], 0, s[30:31]
	s_mov_b32 m0, s34
	s_mov_b64 s[30:31], 0x2000580
	global_load_lds_dwordx4 v[116:117], off
	s_nop 0
	s_nop 0
	s_nop 0
	s_nop 0
	ds_read_b128 a[16:19], v98
	ds_read_b128 a[20:23], v99
	ds_read_b128 a[24:27], v100
	ds_read_b128 a[28:31], v101
	s_waitcnt lgkmcnt(4)
	v_mfma_f32_32x32x16_bf16 v[48:63], a[0:3], a[8:11], v[48:63]
	s_mov_b32 m0, s35
	v_mfma_f32_32x32x16_bf16 v[32:47], a[4:7], a[8:11], v[32:47]
	v_mfma_f32_32x32x16_bf16 v[16:31], a[0:3], a[12:15], v[16:31]
	v_mfma_f32_32x32x16_bf16 v[0:15], a[4:7], a[12:15], v[0:15]
	s_nop 0
	s_nop 0
	s_nop 0
	s_nop 0
	ds_read_b128 a[0:3], v102
	ds_read_b128 a[4:7], v103
	ds_read_b128 a[8:11], v104
	ds_read_b128 a[12:15], v105
	s_waitcnt lgkmcnt(5)
	v_mfma_f32_32x32x16_bf16 v[48:63], a[16:19], a[24:27], v[48:63]
	v_mfma_f32_32x32x16_bf16 v[32:47], a[20:23], a[24:27], v[32:47]
	s_waitcnt lgkmcnt(4)
	v_mfma_f32_32x32x16_bf16 v[16:31], a[16:19], a[28:31], v[16:31]
	v_mfma_f32_32x32x16_bf16 v[0:15], a[20:23], a[28:31], v[0:15]
	s_nop 0
	s_nop 0
	s_nop 0
	s_nop 0
	ds_read_b128 a[16:19], v106
	ds_read_b128 a[20:23], v107
	ds_read_b128 a[24:27], v108
	ds_read_b128 a[28:31], v109
	s_waitcnt lgkmcnt(5)
	v_mfma_f32_32x32x16_bf16 v[48:63], a[0:3], a[8:11], v[48:63]
	v_mfma_f32_32x32x16_bf16 v[32:47], a[4:7], a[8:11], v[32:47]
	s_waitcnt lgkmcnt(4)
	v_mfma_f32_32x32x16_bf16 v[16:31], a[0:3], a[12:15], v[16:31]
	v_mfma_f32_32x32x16_bf16 v[0:15], a[4:7], a[12:15], v[0:15]
	s_nop 0
	s_nop 0
	s_nop 0
	s_nop 0
	s_waitcnt lgkmcnt(1)
	v_mfma_f32_32x32x16_bf16 v[48:63], a[16:19], a[24:27], v[48:63]
	v_mfma_f32_32x32x16_bf16 v[32:47], a[20:23], a[24:27], v[32:47]
	s_waitcnt vmcnt(6)
	s_waitcnt lgkmcnt(0)
	s_barrier
	ds_read_b128 a[12:15], v78 offset:4096
	ds_read_b128 a[8:11], v78
	ds_read_b128 a[4:7], v79 offset:36864
	ds_read_b128 a[0:3], v79 offset:32768
	v_mfma_f32_32x32x16_bf16 v[16:31], a[16:19], a[28:31], v[16:31]
	v_lshl_add_u64 v[116:117], v[66:67], 0, s[30:31]
	s_mov_b64 s[30:31], 0x2004580
	s_mov_b64 exec, vcc
	global_load_lds_dwordx4 v[116:117], off
	s_mov_b64 exec, -1
	v_lshl_add_u64 v[116:117], v[68:69], 0, s[30:31]
	s_mov_b32 m0, s36
	s_mov_b64 s[30:31], 0x2008580
	s_mov_b64 exec, vcc
	global_load_lds_dwordx4 v[116:117], off
	s_mov_b64 exec, -1
	v_lshl_add_u64 v[110:111], v[66:67], 0, s[30:31]
	s_mov_b32 m0, s37
	s_mov_b64 s[30:31], 0x200c580
	s_mov_b64 exec, vcc
	global_load_lds_dwordx4 v[110:111], off
	s_mov_b64 exec, -1
	v_lshl_add_u64 v[110:111], v[68:69], 0, s[30:31]
	s_mov_b32 m0, s38
	s_mov_b64 s[30:31], 0x580
	s_mov_b64 exec, vcc
	global_load_lds_dwordx4 v[110:111], off
	s_mov_b64 exec, -1
	v_lshl_add_u64 v[110:111], v[70:71], 0, s[30:31]
	s_mov_b32 m0, s39
	v_mfma_f32_32x32x16_bf16 v[0:15], a[20:23], a[28:31], v[0:15]
	global_load_lds_dwordx4 v[110:111], off
	v_lshl_add_u64 v[110:111], v[72:73], 0, s[30:31]
	s_mov_b32 m0, s40
	s_mov_b64 s[30:31], 0x2000600
	global_load_lds_dwordx4 v[110:111], off
	s_nop 0
	s_nop 0
	s_nop 0
	s_nop 0
	ds_read_b128 a[16:19], v81 offset:32768
	ds_read_b128 a[20:23], v81 offset:36864
	ds_read_b128 a[24:27], v80
	ds_read_b128 a[28:31], v80 offset:4096
	s_waitcnt lgkmcnt(4)
	v_mfma_f32_32x32x16_bf16 v[48:63], a[0:3], a[8:11], v[48:63]
	s_mov_b32 m0, s0
	v_mfma_f32_32x32x16_bf16 v[32:47], a[4:7], a[8:11], v[32:47]
	v_mfma_f32_32x32x16_bf16 v[16:31], a[0:3], a[12:15], v[16:31]
	v_mfma_f32_32x32x16_bf16 v[0:15], a[4:7], a[12:15], v[0:15]
	s_nop 0
	s_nop 0
	s_nop 0
	s_nop 0
	ds_read_b128 a[0:3], v83 offset:32768
	ds_read_b128 a[4:7], v83 offset:36864
	ds_read_b128 a[8:11], v82
	ds_read_b128 a[12:15], v82 offset:4096
	s_waitcnt lgkmcnt(5)
	v_mfma_f32_32x32x16_bf16 v[48:63], a[16:19], a[24:27], v[48:63]
	v_mfma_f32_32x32x16_bf16 v[32:47], a[20:23], a[24:27], v[32:47]
	s_waitcnt lgkmcnt(4)
	v_mfma_f32_32x32x16_bf16 v[16:31], a[16:19], a[28:31], v[16:31]
	v_mfma_f32_32x32x16_bf16 v[0:15], a[20:23], a[28:31], v[0:15]
	s_nop 0
	s_nop 0
	s_nop 0
	s_nop 0
	ds_read_b128 a[16:19], v85 offset:32768
	ds_read_b128 a[20:23], v85 offset:36864
	ds_read_b128 a[24:27], v84
	ds_read_b128 a[28:31], v84 offset:4096
	s_waitcnt lgkmcnt(5)
	v_mfma_f32_32x32x16_bf16 v[48:63], a[0:3], a[8:11], v[48:63]
	v_mfma_f32_32x32x16_bf16 v[32:47], a[4:7], a[8:11], v[32:47]
	s_waitcnt lgkmcnt(4)
	v_mfma_f32_32x32x16_bf16 v[16:31], a[0:3], a[12:15], v[16:31]
	v_mfma_f32_32x32x16_bf16 v[0:15], a[4:7], a[12:15], v[0:15]
	s_nop 0
	s_nop 0
	s_nop 0
	s_nop 0
	s_waitcnt lgkmcnt(1)
	v_mfma_f32_32x32x16_bf16 v[48:63], a[16:19], a[24:27], v[48:63]
	v_mfma_f32_32x32x16_bf16 v[32:47], a[20:23], a[24:27], v[32:47]
	s_waitcnt vmcnt(6)
	s_waitcnt lgkmcnt(0)
	s_barrier
	ds_read_b128 a[12:15], v78 offset:53248
	ds_read_b128 a[8:11], v78 offset:49152
	ds_read_b128 a[4:7], v86
	ds_read_b128 a[0:3], v88
	v_mfma_f32_32x32x16_bf16 v[16:31], a[16:19], a[28:31], v[16:31]
	v_lshl_add_u64 v[110:111], v[66:67], 0, s[30:31]
	s_mov_b64 s[30:31], 0x2004600
	s_mov_b64 exec, vcc
	global_load_lds_dwordx4 v[110:111], off
	s_mov_b64 exec, -1
	v_lshl_add_u64 v[110:111], v[68:69], 0, s[30:31]
	s_mov_b32 m0, s1
	s_mov_b64 s[30:31], 0x2008600
	s_mov_b64 exec, vcc
	global_load_lds_dwordx4 v[110:111], off
	s_mov_b64 exec, -1
	v_lshl_add_u64 v[110:111], v[66:67], 0, s[30:31]
	s_mov_b32 m0, s2
	s_mov_b64 s[30:31], 0x200c600
	s_mov_b64 exec, vcc
	global_load_lds_dwordx4 v[110:111], off
	s_mov_b64 exec, -1
	v_lshl_add_u64 v[110:111], v[68:69], 0, s[30:31]
	s_mov_b32 m0, s20
	s_mov_b64 s[30:31], 0x600
	s_mov_b64 exec, vcc
	global_load_lds_dwordx4 v[110:111], off
	s_mov_b64 exec, -1
	v_lshl_add_u64 v[110:111], v[70:71], 0, s[30:31]
	s_mov_b32 m0, s21
	v_mfma_f32_32x32x16_bf16 v[0:15], a[20:23], a[28:31], v[0:15]
	global_load_lds_dwordx4 v[110:111], off
	v_lshl_add_u64 v[110:111], v[72:73], 0, s[30:31]
	s_mov_b32 m0, s22
	s_mov_b64 s[30:31], 0x2000680
	global_load_lds_dwordx4 v[110:111], off
	s_nop 0
	s_nop 0
	s_nop 0
	s_nop 0
	ds_read_b128 a[16:19], v89
	ds_read_b128 a[20:23], v87
	ds_read_b128 a[24:27], v80 offset:49152
	ds_read_b128 a[28:31], v80 offset:53248
	s_waitcnt lgkmcnt(4)
	v_mfma_f32_32x32x16_bf16 v[48:63], a[0:3], a[8:11], v[48:63]
	s_mov_b32 m0, s23
	v_mfma_f32_32x32x16_bf16 v[32:47], a[4:7], a[8:11], v[32:47]
	v_mfma_f32_32x32x16_bf16 v[16:31], a[0:3], a[12:15], v[16:31]
	v_mfma_f32_32x32x16_bf16 v[0:15], a[4:7], a[12:15], v[0:15]
	s_nop 0
	s_nop 0
	s_nop 0
	s_nop 0
	ds_read_b128 a[0:3], v91
	ds_read_b128 a[4:7], v90
	ds_read_b128 a[8:11], v82 offset:49152
	ds_read_b128 a[12:15], v82 offset:53248
	s_waitcnt lgkmcnt(5)
	v_mfma_f32_32x32x16_bf16 v[48:63], a[16:19], a[24:27], v[48:63]
	v_mfma_f32_32x32x16_bf16 v[32:47], a[20:23], a[24:27], v[32:47]
	s_waitcnt lgkmcnt(4)
	v_mfma_f32_32x32x16_bf16 v[16:31], a[16:19], a[28:31], v[16:31]
	v_mfma_f32_32x32x16_bf16 v[0:15], a[20:23], a[28:31], v[0:15]
	s_nop 0
	s_nop 0
	s_nop 0
	s_nop 0
	ds_read_b128 a[16:19], v93
	ds_read_b128 a[20:23], v92
	ds_read_b128 a[24:27], v84 offset:49152
	ds_read_b128 a[28:31], v84 offset:53248
	s_waitcnt lgkmcnt(5)
	v_mfma_f32_32x32x16_bf16 v[48:63], a[0:3], a[8:11], v[48:63]
	v_mfma_f32_32x32x16_bf16 v[32:47], a[4:7], a[8:11], v[32:47]
	s_waitcnt lgkmcnt(4)
	v_mfma_f32_32x32x16_bf16 v[16:31], a[0:3], a[12:15], v[16:31]
	v_mfma_f32_32x32x16_bf16 v[0:15], a[4:7], a[12:15], v[0:15]
	s_nop 0
	s_nop 0
	s_nop 0
	s_nop 0
	s_waitcnt lgkmcnt(1)
	v_mfma_f32_32x32x16_bf16 v[48:63], a[16:19], a[24:27], v[48:63]
	v_mfma_f32_32x32x16_bf16 v[32:47], a[20:23], a[24:27], v[32:47]
	s_waitcnt vmcnt(6)
	s_waitcnt lgkmcnt(0)
	s_barrier
	ds_read_b128 a[12:15], v97
	ds_read_b128 a[8:11], v96
	ds_read_b128 a[4:7], v95
	ds_read_b128 a[0:3], v94
	v_mfma_f32_32x32x16_bf16 v[16:31], a[16:19], a[28:31], v[16:31]
	v_lshl_add_u64 v[110:111], v[66:67], 0, s[30:31]
	s_mov_b64 s[30:31], 0x2004680
	s_mov_b64 exec, vcc
	global_load_lds_dwordx4 v[110:111], off
	s_mov_b64 exec, -1
	v_lshl_add_u64 v[110:111], v[68:69], 0, s[30:31]
	s_mov_b32 m0, s24
	s_mov_b64 s[30:31], 0x2008680
	s_mov_b64 exec, vcc
	global_load_lds_dwordx4 v[110:111], off
	s_mov_b64 exec, -1
	v_lshl_add_u64 v[110:111], v[66:67], 0, s[30:31]
	s_mov_b32 m0, s28
	s_mov_b64 s[30:31], 0x200c680
	s_mov_b64 exec, vcc
	global_load_lds_dwordx4 v[110:111], off
	s_mov_b64 exec, -1
	v_lshl_add_u64 v[110:111], v[68:69], 0, s[30:31]
	s_mov_b32 m0, s29
	s_mov_b64 s[28:29], 0x680
	s_mov_b64 exec, vcc
	global_load_lds_dwordx4 v[110:111], off
	s_mov_b64 exec, -1
	v_lshl_add_u64 v[110:111], v[70:71], 0, s[28:29]
	s_mov_b32 m0, s33
	v_mfma_f32_32x32x16_bf16 v[0:15], a[20:23], a[28:31], v[0:15]
	global_load_lds_dwordx4 v[110:111], off
	v_lshl_add_u64 v[110:111], v[72:73], 0, s[28:29]
	s_mov_b32 m0, s34
	s_mov_b64 s[28:29], 0x2000700
	global_load_lds_dwordx4 v[110:111], off
	s_nop 0
	s_nop 0
	s_nop 0
	s_nop 0
	ds_read_b128 a[16:19], v98
	ds_read_b128 a[20:23], v99
	ds_read_b128 a[24:27], v100
	ds_read_b128 a[28:31], v101
	s_waitcnt lgkmcnt(4)
	v_mfma_f32_32x32x16_bf16 v[48:63], a[0:3], a[8:11], v[48:63]
	s_mov_b32 m0, s35
	v_mfma_f32_32x32x16_bf16 v[32:47], a[4:7], a[8:11], v[32:47]
	v_mfma_f32_32x32x16_bf16 v[16:31], a[0:3], a[12:15], v[16:31]
	v_mfma_f32_32x32x16_bf16 v[0:15], a[4:7], a[12:15], v[0:15]
	s_nop 0
	s_nop 0
	s_nop 0
	s_nop 0
	ds_read_b128 a[0:3], v102
	ds_read_b128 a[4:7], v103
	ds_read_b128 a[8:11], v104
	ds_read_b128 a[12:15], v105
	s_waitcnt lgkmcnt(5)
	v_mfma_f32_32x32x16_bf16 v[48:63], a[16:19], a[24:27], v[48:63]
	v_mfma_f32_32x32x16_bf16 v[32:47], a[20:23], a[24:27], v[32:47]
	s_waitcnt lgkmcnt(4)
	v_mfma_f32_32x32x16_bf16 v[16:31], a[16:19], a[28:31], v[16:31]
	v_mfma_f32_32x32x16_bf16 v[0:15], a[20:23], a[28:31], v[0:15]
	s_nop 0
	s_nop 0
	s_nop 0
	s_nop 0
	ds_read_b128 a[16:19], v106
	ds_read_b128 a[20:23], v107
	ds_read_b128 a[24:27], v108
	ds_read_b128 a[28:31], v109
	s_waitcnt lgkmcnt(5)
	v_mfma_f32_32x32x16_bf16 v[48:63], a[0:3], a[8:11], v[48:63]
	v_mfma_f32_32x32x16_bf16 v[32:47], a[4:7], a[8:11], v[32:47]
	s_waitcnt lgkmcnt(4)
	v_mfma_f32_32x32x16_bf16 v[16:31], a[0:3], a[12:15], v[16:31]
	v_mfma_f32_32x32x16_bf16 v[0:15], a[4:7], a[12:15], v[0:15]
	s_nop 0
	s_nop 0
	s_nop 0
	s_nop 0
	s_waitcnt lgkmcnt(1)
	v_mfma_f32_32x32x16_bf16 v[48:63], a[16:19], a[24:27], v[48:63]
	v_mfma_f32_32x32x16_bf16 v[32:47], a[20:23], a[24:27], v[32:47]
	s_waitcnt vmcnt(6)
	s_waitcnt lgkmcnt(0)
	s_barrier
	ds_read_b128 a[12:15], v78 offset:4096
	ds_read_b128 a[8:11], v78
	ds_read_b128 a[4:7], v79 offset:36864
	ds_read_b128 a[0:3], v79 offset:32768
	v_mfma_f32_32x32x16_bf16 v[16:31], a[16:19], a[28:31], v[16:31]
	v_lshl_add_u64 v[110:111], v[66:67], 0, s[28:29]
	s_mov_b64 s[28:29], 0x2004700
	s_mov_b64 exec, vcc
	global_load_lds_dwordx4 v[110:111], off
	s_mov_b64 exec, -1
	v_lshl_add_u64 v[110:111], v[68:69], 0, s[28:29]
	s_mov_b32 m0, s36
	s_mov_b64 s[28:29], 0x2008700
	s_mov_b64 exec, vcc
	global_load_lds_dwordx4 v[110:111], off
	s_mov_b64 exec, -1
	v_lshl_add_u64 v[110:111], v[66:67], 0, s[28:29]
	s_mov_b32 m0, s37
	s_mov_b64 s[28:29], 0x200c700
	s_mov_b64 exec, vcc
	global_load_lds_dwordx4 v[110:111], off
	s_mov_b64 exec, -1
	v_lshl_add_u64 v[110:111], v[68:69], 0, s[28:29]
	s_mov_b32 m0, s38
	s_mov_b64 s[28:29], 0x700
	s_mov_b64 exec, vcc
	global_load_lds_dwordx4 v[110:111], off
	s_mov_b64 exec, -1
	v_lshl_add_u64 v[110:111], v[70:71], 0, s[28:29]
	s_mov_b32 m0, s39
	v_mfma_f32_32x32x16_bf16 v[0:15], a[20:23], a[28:31], v[0:15]
	global_load_lds_dwordx4 v[110:111], off
	v_lshl_add_u64 v[110:111], v[72:73], 0, s[28:29]
	s_mov_b32 m0, s40
	s_mov_b64 s[28:29], 0x2000780
	global_load_lds_dwordx4 v[110:111], off
	s_nop 0
	s_nop 0
	s_nop 0
	s_nop 0
	ds_read_b128 a[16:19], v81 offset:32768
	ds_read_b128 a[20:23], v81 offset:36864
	ds_read_b128 a[24:27], v80
	ds_read_b128 a[28:31], v80 offset:4096
	s_waitcnt lgkmcnt(4)
	v_mfma_f32_32x32x16_bf16 v[48:63], a[0:3], a[8:11], v[48:63]
	s_mov_b32 m0, s0
	v_mfma_f32_32x32x16_bf16 v[32:47], a[4:7], a[8:11], v[32:47]
	v_mfma_f32_32x32x16_bf16 v[16:31], a[0:3], a[12:15], v[16:31]
	v_mfma_f32_32x32x16_bf16 v[0:15], a[4:7], a[12:15], v[0:15]
	s_nop 0
	s_nop 0
	s_nop 0
	s_nop 0
	ds_read_b128 a[0:3], v83 offset:32768
	ds_read_b128 a[4:7], v83 offset:36864
	ds_read_b128 a[8:11], v82
	ds_read_b128 a[12:15], v82 offset:4096
	s_waitcnt lgkmcnt(5)
	v_mfma_f32_32x32x16_bf16 v[48:63], a[16:19], a[24:27], v[48:63]
	v_mfma_f32_32x32x16_bf16 v[32:47], a[20:23], a[24:27], v[32:47]
	s_waitcnt lgkmcnt(4)
	v_mfma_f32_32x32x16_bf16 v[16:31], a[16:19], a[28:31], v[16:31]
	v_mfma_f32_32x32x16_bf16 v[0:15], a[20:23], a[28:31], v[0:15]
	s_nop 0
	s_nop 0
	s_nop 0
	s_nop 0
	ds_read_b128 a[16:19], v85 offset:32768
	ds_read_b128 a[20:23], v85 offset:36864
	ds_read_b128 a[24:27], v84
	ds_read_b128 a[28:31], v84 offset:4096
	s_waitcnt lgkmcnt(5)
	v_mfma_f32_32x32x16_bf16 v[48:63], a[0:3], a[8:11], v[48:63]
	v_mfma_f32_32x32x16_bf16 v[32:47], a[4:7], a[8:11], v[32:47]
	s_waitcnt lgkmcnt(4)
	v_mfma_f32_32x32x16_bf16 v[16:31], a[0:3], a[12:15], v[16:31]
	v_mfma_f32_32x32x16_bf16 v[0:15], a[4:7], a[12:15], v[0:15]
	s_nop 0
	s_nop 0
	s_nop 0
	s_nop 0
	s_waitcnt lgkmcnt(1)
	v_mfma_f32_32x32x16_bf16 v[48:63], a[16:19], a[24:27], v[48:63]
	v_mfma_f32_32x32x16_bf16 v[32:47], a[20:23], a[24:27], v[32:47]
	s_waitcnt vmcnt(6)
	s_waitcnt lgkmcnt(0)
	s_barrier
	ds_read_b128 a[12:15], v78 offset:53248
	ds_read_b128 a[8:11], v78 offset:49152
	ds_read_b128 a[4:7], v86
	ds_read_b128 a[0:3], v88
	v_mfma_f32_32x32x16_bf16 v[16:31], a[16:19], a[28:31], v[16:31]
	v_lshl_add_u64 v[110:111], v[66:67], 0, s[28:29]
	s_mov_b64 s[28:29], 0x2004780
	s_mov_b64 exec, vcc
	global_load_lds_dwordx4 v[110:111], off
	s_mov_b64 exec, -1
	v_lshl_add_u64 v[110:111], v[68:69], 0, s[28:29]
	s_mov_b32 m0, s1
	s_mov_b64 s[0:1], 0x2008780
	s_mov_b64 exec, vcc
	global_load_lds_dwordx4 v[110:111], off
	s_mov_b64 exec, -1
	v_lshl_add_u64 v[66:67], v[66:67], 0, s[0:1]
	s_mov_b32 m0, s2
	s_mov_b64 s[0:1], 0x200c780
	s_mov_b64 exec, vcc
	global_load_lds_dwordx4 v[66:67], off
	s_mov_b64 exec, -1
	v_lshl_add_u64 v[66:67], v[68:69], 0, s[0:1]
	s_mov_b32 m0, s20
	s_mov_b64 s[0:1], 0x780
	s_mov_b64 exec, vcc
	global_load_lds_dwordx4 v[66:67], off
	s_mov_b64 exec, -1
	v_lshl_add_u64 v[66:67], v[70:71], 0, s[0:1]
	s_mov_b32 m0, s21
	v_mfma_f32_32x32x16_bf16 v[0:15], a[20:23], a[28:31], v[0:15]
	global_load_lds_dwordx4 v[66:67], off
	v_lshl_add_u64 v[66:67], v[72:73], 0, s[0:1]
	s_mov_b32 m0, s22
	v_readlane_b32 s0, v215, 52
	global_load_lds_dwordx4 v[66:67], off
	s_nop 0
	s_nop 0
	s_nop 0
	s_nop 0
	ds_read_b128 a[16:19], v89
	ds_read_b128 a[20:23], v87
	ds_read_b128 a[24:27], v80 offset:49152
	ds_read_b128 a[28:31], v80 offset:53248
	s_waitcnt lgkmcnt(4)
	v_mfma_f32_32x32x16_bf16 v[48:63], a[0:3], a[8:11], v[48:63]
	v_readlane_b32 s1, v215, 53
	s_mov_b32 s2, 0
	v_mfma_f32_32x32x16_bf16 v[32:47], a[4:7], a[8:11], v[32:47]
	v_mfma_f32_32x32x16_bf16 v[16:31], a[0:3], a[12:15], v[16:31]
	v_mfma_f32_32x32x16_bf16 v[0:15], a[4:7], a[12:15], v[0:15]
	s_nop 0
	s_nop 0
	s_nop 0
	s_nop 0
	ds_read_b128 a[0:3], v91
	ds_read_b128 a[4:7], v90
	ds_read_b128 a[8:11], v82 offset:49152
	ds_read_b128 a[12:15], v82 offset:53248
	s_waitcnt lgkmcnt(5)
	v_mfma_f32_32x32x16_bf16 v[48:63], a[16:19], a[24:27], v[48:63]
	v_mfma_f32_32x32x16_bf16 v[32:47], a[20:23], a[24:27], v[32:47]
	s_waitcnt lgkmcnt(4)
	v_mfma_f32_32x32x16_bf16 v[16:31], a[16:19], a[28:31], v[16:31]
	v_mfma_f32_32x32x16_bf16 v[0:15], a[20:23], a[28:31], v[0:15]
	s_nop 0
	s_nop 0
	s_nop 0
	s_nop 0
	ds_read_b128 a[16:19], v93
	ds_read_b128 a[20:23], v92
	ds_read_b128 a[24:27], v84 offset:49152
	ds_read_b128 a[28:31], v84 offset:53248
	s_waitcnt lgkmcnt(5)
	v_mfma_f32_32x32x16_bf16 v[48:63], a[0:3], a[8:11], v[48:63]
	v_mfma_f32_32x32x16_bf16 v[32:47], a[4:7], a[8:11], v[32:47]
	s_waitcnt lgkmcnt(4)
	v_mfma_f32_32x32x16_bf16 v[16:31], a[0:3], a[12:15], v[16:31]
	v_mfma_f32_32x32x16_bf16 v[0:15], a[4:7], a[12:15], v[0:15]
	s_nop 0
	s_nop 0
	s_nop 0
	s_nop 0
	s_waitcnt lgkmcnt(1)
	v_mfma_f32_32x32x16_bf16 v[48:63], a[16:19], a[24:27], v[48:63]
	v_mfma_f32_32x32x16_bf16 v[32:47], a[20:23], a[24:27], v[32:47]
	s_waitcnt vmcnt(6)
	s_waitcnt lgkmcnt(0)
	s_barrier
	ds_read_b128 a[12:15], v97
	ds_read_b128 a[8:11], v96
	ds_read_b128 a[4:7], v95
	ds_read_b128 a[0:3], v94
	v_mfma_f32_32x32x16_bf16 v[16:31], a[16:19], a[28:31], v[16:31]
	v_mfma_f32_32x32x16_bf16 v[0:15], a[20:23], a[28:31], v[0:15]
	s_nop 0
	s_nop 0
	s_nop 0
	s_nop 0
	ds_read_b128 a[16:19], v98
	ds_read_b128 a[20:23], v99
	ds_read_b128 a[24:27], v100
	ds_read_b128 a[28:31], v101
	s_waitcnt lgkmcnt(4)
	v_mfma_f32_32x32x16_bf16 v[48:63], a[0:3], a[8:11], v[48:63]
	v_mfma_f32_32x32x16_bf16 v[32:47], a[4:7], a[8:11], v[32:47]
	v_mfma_f32_32x32x16_bf16 v[16:31], a[0:3], a[12:15], v[16:31]
	v_mfma_f32_32x32x16_bf16 v[0:15], a[4:7], a[12:15], v[0:15]
	s_nop 0
	s_nop 0
	s_nop 0
	s_nop 0
	ds_read_b128 a[0:3], v102
	ds_read_b128 a[4:7], v103
	ds_read_b128 a[8:11], v104
	ds_read_b128 a[12:15], v105
	s_waitcnt lgkmcnt(5)
	v_mfma_f32_32x32x16_bf16 v[48:63], a[16:19], a[24:27], v[48:63]
	v_mfma_f32_32x32x16_bf16 v[32:47], a[20:23], a[24:27], v[32:47]
	s_waitcnt lgkmcnt(4)
	v_mfma_f32_32x32x16_bf16 v[16:31], a[16:19], a[28:31], v[16:31]
	v_mfma_f32_32x32x16_bf16 v[0:15], a[20:23], a[28:31], v[0:15]
	s_nop 0
	s_nop 0
	s_nop 0
	s_nop 0
	ds_read_b128 a[16:19], v106
	ds_read_b128 a[20:23], v107
	ds_read_b128 a[24:27], v108
	ds_read_b128 a[28:31], v109
	s_waitcnt lgkmcnt(5)
	v_mfma_f32_32x32x16_bf16 v[48:63], a[0:3], a[8:11], v[48:63]
	v_mfma_f32_32x32x16_bf16 v[32:47], a[4:7], a[8:11], v[32:47]
	s_waitcnt lgkmcnt(4)
	v_mfma_f32_32x32x16_bf16 v[16:31], a[0:3], a[12:15], v[16:31]
	v_mfma_f32_32x32x16_bf16 v[0:15], a[4:7], a[12:15], v[0:15]
	s_nop 0
	s_nop 0
	s_nop 0
	s_nop 0
	s_waitcnt lgkmcnt(1)
	v_mfma_f32_32x32x16_bf16 v[48:63], a[16:19], a[24:27], v[48:63]
	v_mfma_f32_32x32x16_bf16 v[32:47], a[20:23], a[24:27], v[32:47]
	s_waitcnt vmcnt(0)
	s_waitcnt lgkmcnt(0)
	s_barrier
	ds_read_b128 a[12:15], v78 offset:4096
	ds_read_b128 a[8:11], v78
	ds_read_b128 a[4:7], v79 offset:36864
	ds_read_b128 a[0:3], v79 offset:32768
	v_mfma_f32_32x32x16_bf16 v[16:31], a[16:19], a[28:31], v[16:31]
	v_mfma_f32_32x32x16_bf16 v[0:15], a[20:23], a[28:31], v[0:15]
	s_nop 0
	s_nop 0
	s_nop 0
	s_nop 0
	ds_read_b128 a[16:19], v81 offset:32768
	ds_read_b128 a[20:23], v81 offset:36864
	ds_read_b128 a[24:27], v80
	ds_read_b128 a[28:31], v80 offset:4096
	s_waitcnt lgkmcnt(4)
	v_mfma_f32_32x32x16_bf16 v[48:63], a[0:3], a[8:11], v[48:63]
	v_mfma_f32_32x32x16_bf16 v[32:47], a[4:7], a[8:11], v[32:47]
	v_mfma_f32_32x32x16_bf16 v[16:31], a[0:3], a[12:15], v[16:31]
	v_mfma_f32_32x32x16_bf16 v[0:15], a[4:7], a[12:15], v[0:15]
	s_nop 0
	s_nop 0
	s_nop 0
	s_nop 0
	ds_read_b128 a[0:3], v83 offset:32768
	ds_read_b128 a[4:7], v83 offset:36864
	ds_read_b128 a[8:11], v82
	ds_read_b128 a[12:15], v82 offset:4096
	s_waitcnt lgkmcnt(5)
	v_mfma_f32_32x32x16_bf16 v[48:63], a[16:19], a[24:27], v[48:63]
	v_mfma_f32_32x32x16_bf16 v[32:47], a[20:23], a[24:27], v[32:47]
	s_waitcnt lgkmcnt(4)
	v_mfma_f32_32x32x16_bf16 v[16:31], a[16:19], a[28:31], v[16:31]
	v_mfma_f32_32x32x16_bf16 v[0:15], a[20:23], a[28:31], v[0:15]
	s_nop 0
	s_nop 0
	s_nop 0
	s_waitcnt lgkmcnt(1)
	v_mfma_f32_32x32x16_bf16 v[48:63], a[0:3], a[8:11], v[48:63]
	v_mfma_f32_32x32x16_bf16 v[32:47], a[4:7], a[8:11], v[32:47]
	s_nop 0
	s_waitcnt lgkmcnt(0)
	v_mfma_f32_32x32x16_bf16 v[0:15], a[4:7], a[12:15], v[0:15]
	v_mfma_f32_32x32x16_bf16 v[16:31], a[0:3], a[12:15], v[16:31]
	ds_read_b128 v[66:69], v85 offset:32768
	ds_read_b128 v[70:73], v84
	ds_read_b128 v[78:81], v85 offset:36864
	ds_read_b128 v[82:85], v84 offset:4096
	s_waitcnt lgkmcnt(0)
	s_barrier
	s_waitcnt lgkmcnt(0)
	v_mfma_f32_32x32x16_bf16 v[48:63], v[66:69], v[70:73], v[48:63]
	v_mfma_f32_32x32x16_bf16 v[32:47], v[78:81], v[70:73], v[32:47]
	s_nop 10
	ds_write_b128 v64, v[48:51]
	ds_write_b128 v64, v[52:55] offset:32
	ds_write_b128 v64, v[56:59] offset:64
	ds_write_b128 v64, v[60:63] offset:96
	ds_write_b128 v64, v[32:35] offset:128
	v_mfma_f32_32x32x16_bf16 v[0:15], v[78:81], v[82:85], v[0:15]
	v_mfma_f32_32x32x16_bf16 v[16:31], v[66:69], v[82:85], v[16:31]
	ds_write_b128 v64, v[36:39] offset:160
	ds_write_b128 v64, v[40:43] offset:192
	ds_write_b128 v64, v[44:47] offset:224
	s_nop 8
	ds_write_b128 v64, v[16:19] offset:16896
	ds_write_b128 v64, v[20:23] offset:16928
	ds_write_b128 v64, v[24:27] offset:16960
	ds_write_b128 v64, v[28:31] offset:16992
	ds_write_b128 v64, v[0:3] offset:17024
	ds_write_b128 v64, v[4:7] offset:17056
	ds_write_b128 v64, v[8:11] offset:17088
	ds_write_b128 v64, v[12:15] offset:17120
	s_waitcnt lgkmcnt(0)
	s_barrier
	v_lshl_or_b32 v0, v75, 2, s53
	v_ashrrev_i32_e32 v1, 31, v0
	v_lshl_add_u32 v4, v75, 4, 0
	v_lshl_add_u64 v[6:7], v[0:1], 2, s[92:93]
	v_lshl_add_u64 v[8:9], v[0:1], 1, s[0:1]
	v_cmp_eq_u32_e64 s[0:1], 0, v75
	s_branch .LBB0_244
